# cooperative grid.sync: barrier-pointer s_load and expected-count load issued before the L2 write-back wait (on top of the invalidate hoists)
# speedup vs baseline: 1.0097x; 1.0016x over previous
; __global__ void __launch_bounds__(NTHR, 2) fwd_megakernel(Params p) {
;     ...
;     grid.sync();
.LBB0_102:
	v_lshrrev_b32_e32 v1, 20, v0
	v_lshrrev_b32_e32 v0, 10, v0
	v_or_b32_e32 v0, v0, v1
	s_movk_i32 s0, 0x3ff
	v_and_or_b32 v0, v0, s0, v170
	v_cmp_eq_u32_e32 vcc, 0, v0
	s_barrier
	s_and_saveexec_b64 s[0:1], vcc
	s_cbranch_execz .LBB0_112
	s_load_dwordx2 s[4:5], s[12:13], 0x58
	v_mov_b32_e32 v2, 0
	s_mov_b64 s[6:7], exec
	v_mbcnt_lo_u32_b32 v1, s6, 0
	v_mbcnt_hi_u32_b32 v1, s7, v1
	s_waitcnt lgkmcnt(0)
	global_load_dword v0, v2, s[4:5] offset:40
	buffer_wbl2 sc1
	s_waitcnt vmcnt(0)
	v_cmp_eq_u32_e32 vcc, 0, v1
	s_and_saveexec_b64 s[8:9], vcc
	s_cbranch_execz .LBB0_105
	s_bcnt1_i32_b64 s6, s[6:7]
	v_mov_b32_e32 v3, s6
	global_atomic_add v3, v2, v3, s[4:5] offset:32 sc0
